# v98 + s_setprio 1 around the QK and PV MFMA blocks of the banded tile loops
# speedup vs baseline: 1.0011x; 1.0011x over previous
.LBB0_903:
	v_sub_f32_e32 v0, v0, v213
	v_exp_f32_e32 v0, v0
	v_sub_f32_e32 v1, v1, v213
	v_exp_f32_e32 v1, v1
	v_sub_f32_e32 v2, v2, v213
	v_exp_f32_e32 v2, v2
	v_sub_f32_e32 v3, v3, v213
	v_exp_f32_e32 v3, v3
	v_sub_f32_e32 v4, v4, v213
	v_add_f32_e32 v32, 0, v0
	v_exp_f32_e32 v4, v4
	v_sub_f32_e32 v5, v5, v213
	v_add_f32_e32 v32, v1, v32
	v_exp_f32_e32 v5, v5
	v_sub_f32_e32 v6, v6, v213
	v_add_f32_e32 v32, v2, v32
	v_exp_f32_e32 v6, v6
	v_sub_f32_e32 v7, v7, v213
	v_add_f32_e32 v32, v3, v32
	v_exp_f32_e32 v7, v7
	v_sub_f32_e32 v8, v8, v213
	v_add_f32_e32 v32, v4, v32
	v_exp_f32_e32 v66, v8
	v_add_f32_e32 v32, v5, v32
	v_add_f32_e32 v32, v6, v32
	v_add_f32_e32 v32, v7, v32
	v_sub_f32_e32 v9, v9, v213
	v_add_f32_e32 v8, v66, v32
	v_exp_f32_e32 v32, v9
	v_sub_f32_e32 v9, v10, v213
	v_exp_f32_e32 v67, v9
	v_sub_f32_e32 v9, v11, v213
	v_exp_f32_e32 v68, v9
	v_sub_f32_e32 v9, v12, v213
	v_exp_f32_e32 v69, v9
	v_sub_f32_e32 v9, v13, v213
	v_add_f32_e32 v8, v32, v8
	v_exp_f32_e32 v70, v9
	v_sub_f32_e32 v9, v14, v213
	v_add_f32_e32 v8, v67, v8
	v_exp_f32_e32 v71, v9
	v_sub_f32_e32 v9, v15, v213
	v_add_f32_e32 v8, v68, v8
	v_exp_f32_e32 v15, v9
	v_sub_f32_e32 v9, v16, v213
	v_add_f32_e32 v8, v69, v8
	v_exp_f32_e32 v16, v9
	v_sub_f32_e32 v9, v17, v213
	v_add_f32_e32 v8, v70, v8
	v_exp_f32_e32 v17, v9
	v_sub_f32_e32 v9, v18, v213
	v_add_f32_e32 v8, v71, v8
	v_exp_f32_e32 v18, v9
	v_sub_f32_e32 v9, v19, v213
	v_add_f32_e32 v8, v15, v8
	v_exp_f32_e32 v19, v9
	v_sub_f32_e32 v9, v20, v213
	v_add_f32_e32 v8, v16, v8
	v_exp_f32_e32 v20, v9
	v_sub_f32_e32 v9, v21, v213
	v_add_f32_e32 v8, v17, v8
	v_exp_f32_e32 v21, v9
	v_sub_f32_e32 v9, v22, v213
	v_add_f32_e32 v8, v18, v8
	v_exp_f32_e32 v22, v9
	v_sub_f32_e32 v9, v23, v213
	v_add_f32_e32 v8, v19, v8
	v_exp_f32_e32 v23, v9
	v_sub_f32_e32 v9, v24, v213
	v_add_f32_e32 v8, v20, v8
	v_exp_f32_e32 v24, v9
	v_sub_f32_e32 v9, v25, v213
	v_add_f32_e32 v8, v21, v8
	v_exp_f32_e32 v25, v9
	v_sub_f32_e32 v9, v26, v213
	v_add_f32_e32 v8, v22, v8
	v_exp_f32_e32 v26, v9
	v_sub_f32_e32 v9, v27, v213
	v_add_f32_e32 v8, v23, v8
	v_exp_f32_e32 v27, v9
	v_sub_f32_e32 v9, v28, v213
	v_add_f32_e32 v8, v24, v8
	v_exp_f32_e32 v28, v9
	v_sub_f32_e32 v9, v29, v213
	v_add_f32_e32 v8, v25, v8
	v_exp_f32_e32 v29, v9
	v_sub_f32_e32 v9, v30, v213
	v_add_f32_e32 v8, v26, v8
	v_exp_f32_e32 v30, v9
	v_sub_f32_e32 v9, v31, v213
	v_add_f32_e32 v8, v27, v8
	v_exp_f32_e32 v31, v9
	v_add_f32_e32 v8, v28, v8
	v_add_f32_e32 v8, v29, v8
	v_add_f32_e32 v8, v30, v8
	v_add_f32_e32 v72, v31, v8
	v_cvt_pk_bf16_f32 v8, v0, v1
	v_cvt_pk_bf16_f32 v9, v2, v3
	v_cvt_pk_bf16_f32 v10, v4, v5
	v_cvt_pk_bf16_f32 v11, v6, v7
	v_cvt_pk_bf16_f32 v12, v66, v32
	v_cvt_pk_bf16_f32 v13, v67, v68
	s_setprio 1
	s_waitcnt vmcnt(15)
	v_mfma_f32_32x32x16_bf16 v[50:65], v[174:177], v[8:11], v[50:65]
	v_cvt_pk_bf16_f32 v14, v69, v70
	v_cvt_pk_bf16_f32 v15, v71, v15
	v_cvt_pk_bf16_f32 v4, v16, v17
	v_cvt_pk_bf16_f32 v5, v18, v19
	v_cvt_pk_bf16_f32 v6, v20, v21
	v_cvt_pk_bf16_f32 v7, v22, v23
	v_cvt_pk_bf16_f32 v0, v24, v25
	s_waitcnt vmcnt(11)
	v_mfma_f32_32x32x16_bf16 v[34:49], v[158:161], v[8:11], v[34:49]
	v_cvt_pk_bf16_f32 v1, v26, v27
	v_cvt_pk_bf16_f32 v2, v28, v29
	v_cvt_pk_bf16_f32 v3, v30, v31
	v_add_f32_e32 v214, v214, v72
	s_add_i32 s9, s9, 64
	s_and_b64 vcc, exec, s[42:43]
	v_mfma_f32_32x32x16_bf16 v[50:65], v[170:173], v[12:15], v[50:65]
	s_waitcnt vmcnt(10)
	v_mfma_f32_32x32x16_bf16 v[34:49], v[154:157], v[12:15], v[34:49]
	v_mfma_f32_32x32x16_bf16 v[50:65], v[166:169], v[4:7], v[50:65]
	s_waitcnt vmcnt(9)
	v_mfma_f32_32x32x16_bf16 v[34:49], v[150:153], v[4:7], v[34:49]
	v_mfma_f32_32x32x16_bf16 v[50:65], v[162:165], v[0:3], v[50:65]
	s_waitcnt vmcnt(8)
	v_mfma_f32_32x32x16_bf16 v[34:49], v[146:149], v[0:3], v[34:49]
	v_lshl_add_u64 v[16:17], v[206:207], 0, s[40:41]
	global_load_dwordx4 v[174:177], v[16:17], off offset:-4096
	global_load_dwordx4 v[170:173], v[16:17], off offset:-3072
	global_load_dwordx4 v[166:169], v[16:17], off offset:-2048
	global_load_dwordx4 v[162:165], v[16:17], off offset:-1024
	global_load_dwordx4 v[158:161], v[16:17], off
	global_load_dwordx4 v[154:157], v[16:17], off offset:1024
	global_load_dwordx4 v[150:153], v[16:17], off offset:2048
	global_load_dwordx4 v[146:149], v[16:17], off offset:3072
	s_setprio 0
	s_cbranch_vccnz .LBB0_899
.LBB0_904:
	s_waitcnt vmcnt(8)
	s_setprio 1
	v_mfma_f32_32x32x16_bf16 v[66:81], v[142:145], v[98:101], 0
	s_mov_b32 s10, s52
	s_add_i32 s52, s52, 1
	s_cmp_ge_u32 s52, s51
	s_cselect_b64 s[42:43], -1, 0
	s_cmp_lt_u32 s52, s51
	v_mfma_f32_32x32x16_bf16 v[82:97], v[126:129], v[98:101], 0
	s_cselect_b32 s16, s52, s10
	s_lshl_b64 s[40:41], s[16:17], 13
	s_and_b32 s67, s42, s66
	s_cmp_lg_u32 s67, 0
	s_cselect_b32 s40, s60, s40
	s_cselect_b32 s41, s61, s41
	v_mfma_f32_32x32x16_bf16 v[66:81], v[138:141], v[102:105], v[66:81]
	v_lshl_add_u64 v[0:1], v[204:205], 0, s[40:41]
	global_load_dwordx4 v[142:145], v[0:1], off
	global_load_dwordx4 v[138:141], v[0:1], off offset:1024
	s_cmp_lt_u32 s9, s53
	s_cselect_b64 s[10:11], -1, 0
	s_cmp_gt_i32 s9, s54
	s_cselect_b64 s[44:45], -1, 0
	s_and_b64 s[10:11], s[10:11], s[44:45]
	v_mfma_f32_32x32x16_bf16 v[82:97], v[122:125], v[102:105], v[82:97]
	s_mov_b64 s[44:45], -1
	v_mfma_f32_32x32x16_bf16 v[66:81], v[134:137], v[106:109], v[66:81]
	v_mfma_f32_32x32x16_bf16 v[82:97], v[118:121], v[106:109], v[82:97]
	v_mfma_f32_32x32x16_bf16 v[66:81], v[130:133], v[110:113], v[66:81]
	global_load_dwordx4 v[134:137], v[0:1], off offset:2048
	global_load_dwordx4 v[130:133], v[0:1], off offset:3072
	v_add_co_u32_e32 v0, vcc, s79, v0
	s_nop 1
	v_addc_co_u32_e32 v1, vcc, 0, v1, vcc
	global_load_dwordx4 v[126:129], v[0:1], off
	global_load_dwordx4 v[122:125], v[0:1], off offset:1024
	v_mfma_f32_32x32x16_bf16 v[82:97], v[114:117], v[110:113], v[82:97]
	s_setprio 0
	global_load_dwordx4 v[118:121], v[0:1], off offset:2048
	global_load_dwordx4 v[114:117], v[0:1], off offset:3072
	s_cmp_lg_u32 s67, 0
	s_cbranch_scc0 .Lpf_nq
	v_lshlrev_b32_e32 v16, 7, v178
	v_mov_b32_e32 v17, 0
	v_lshl_add_u64 v[16:17], v[180:181], 0, v[16:17]
	v_lshl_add_u64 v[16:17], v[16:17], 0, s[62:63]
	global_load_dwordx4 v[98:101], v[16:17], off
	global_load_dwordx4 v[102:105], v[16:17], off offset:32
	global_load_dwordx4 v[106:109], v[16:17], off offset:64
	global_load_dwordx4 v[110:113], v[16:17], off offset:96
	s_load_dword s101, s[70:71], s69
	s_mov_b32 s100, 1

.LBB0_918:
	v_sub_f32_e32 v0, v0, v210
	v_exp_f32_e32 v0, v0
	v_sub_f32_e32 v1, v1, v210
	v_exp_f32_e32 v1, v1
	v_sub_f32_e32 v2, v2, v210
	v_exp_f32_e32 v2, v2
	v_sub_f32_e32 v3, v3, v210
	v_exp_f32_e32 v3, v3
	v_sub_f32_e32 v4, v4, v210
	v_add_f32_e32 v66, 0, v0
	v_exp_f32_e32 v4, v4
	v_sub_f32_e32 v5, v5, v210
	v_add_f32_e32 v66, v1, v66
	v_exp_f32_e32 v5, v5
	v_sub_f32_e32 v6, v6, v210
	v_add_f32_e32 v66, v2, v66
	v_exp_f32_e32 v6, v6
	v_sub_f32_e32 v7, v7, v210
	v_add_f32_e32 v66, v3, v66
	v_exp_f32_e32 v7, v7
	v_sub_f32_e32 v8, v8, v210
	v_add_f32_e32 v66, v4, v66
	v_exp_f32_e32 v67, v8
	v_add_f32_e32 v66, v5, v66
	v_add_f32_e32 v66, v6, v66
	v_add_f32_e32 v66, v7, v66
	v_sub_f32_e32 v9, v9, v210
	v_add_f32_e32 v8, v67, v66
	v_exp_f32_e32 v66, v9
	v_sub_f32_e32 v9, v10, v210
	v_exp_f32_e32 v68, v9
	v_sub_f32_e32 v9, v11, v210
	v_exp_f32_e32 v69, v9
	v_sub_f32_e32 v9, v12, v210
	v_exp_f32_e32 v70, v9
	v_sub_f32_e32 v9, v13, v210
	v_add_f32_e32 v8, v66, v8
	v_exp_f32_e32 v71, v9
	v_sub_f32_e32 v9, v14, v210
	v_add_f32_e32 v8, v68, v8
	v_exp_f32_e32 v72, v9
	v_sub_f32_e32 v9, v15, v210
	v_add_f32_e32 v8, v69, v8
	v_exp_f32_e32 v15, v9
	v_sub_f32_e32 v9, v16, v210
	v_add_f32_e32 v8, v70, v8
	v_exp_f32_e32 v16, v9
	v_sub_f32_e32 v9, v17, v210
	v_add_f32_e32 v8, v71, v8
	v_exp_f32_e32 v17, v9
	v_sub_f32_e32 v9, v18, v210
	v_add_f32_e32 v8, v72, v8
	v_exp_f32_e32 v18, v9
	v_sub_f32_e32 v9, v19, v210
	v_add_f32_e32 v8, v15, v8
	v_exp_f32_e32 v19, v9
	v_sub_f32_e32 v9, v20, v210
	v_add_f32_e32 v8, v16, v8
	v_exp_f32_e32 v20, v9
	v_sub_f32_e32 v9, v21, v210
	v_add_f32_e32 v8, v17, v8
	v_exp_f32_e32 v21, v9
	v_sub_f32_e32 v9, v22, v210
	v_add_f32_e32 v8, v18, v8
	v_exp_f32_e32 v22, v9
	v_sub_f32_e32 v9, v23, v210
	v_add_f32_e32 v8, v19, v8
	v_exp_f32_e32 v23, v9
	v_sub_f32_e32 v9, v24, v210
	v_add_f32_e32 v8, v20, v8
	v_exp_f32_e32 v24, v9
	v_sub_f32_e32 v9, v25, v210
	v_add_f32_e32 v8, v21, v8
	v_exp_f32_e32 v25, v9
	v_sub_f32_e32 v9, v26, v210
	v_add_f32_e32 v8, v22, v8
	v_exp_f32_e32 v26, v9
	v_sub_f32_e32 v9, v27, v210
	v_add_f32_e32 v8, v23, v8
	v_exp_f32_e32 v27, v9
	v_sub_f32_e32 v9, v28, v210
	v_add_f32_e32 v8, v24, v8
	v_exp_f32_e32 v28, v9
	v_sub_f32_e32 v9, v29, v210
	v_add_f32_e32 v8, v25, v8
	v_exp_f32_e32 v29, v9
	v_sub_f32_e32 v9, v30, v210
	v_add_f32_e32 v8, v26, v8
	v_exp_f32_e32 v30, v9
	v_sub_f32_e32 v9, v31, v210
	v_add_f32_e32 v8, v27, v8
	v_exp_f32_e32 v31, v9
	v_add_f32_e32 v8, v28, v8
	v_add_f32_e32 v8, v29, v8
	v_add_f32_e32 v8, v30, v8
	v_add_f32_e32 v73, v31, v8
	v_cvt_pk_bf16_f32 v8, v0, v1
	v_cvt_pk_bf16_f32 v9, v2, v3
	v_cvt_pk_bf16_f32 v10, v4, v5
	v_cvt_pk_bf16_f32 v11, v6, v7
	v_cvt_pk_bf16_f32 v12, v67, v66
	v_cvt_pk_bf16_f32 v13, v68, v69
	s_setprio 1
	s_waitcnt vmcnt(15)
	v_mfma_f32_32x32x16_bf16 v[50:65], v[174:177], v[8:11], v[50:65]
	v_cvt_pk_bf16_f32 v14, v70, v71
	v_cvt_pk_bf16_f32 v15, v72, v15
	v_cvt_pk_bf16_f32 v4, v16, v17
	v_cvt_pk_bf16_f32 v5, v18, v19
	v_cvt_pk_bf16_f32 v6, v20, v21
	v_cvt_pk_bf16_f32 v7, v22, v23
	v_cvt_pk_bf16_f32 v0, v24, v25
	s_waitcnt vmcnt(11)
	v_mfma_f32_32x32x16_bf16 v[34:49], v[158:161], v[8:11], v[34:49]
	v_cvt_pk_bf16_f32 v1, v26, v27
	v_cvt_pk_bf16_f32 v2, v28, v29
	v_cvt_pk_bf16_f32 v3, v30, v31
	v_add_f32_e32 v211, v211, v73
	s_add_i32 s33, s33, 64
	s_and_b64 vcc, exec, s[50:51]
	v_mfma_f32_32x32x16_bf16 v[50:65], v[170:173], v[12:15], v[50:65]
	s_waitcnt vmcnt(10)
	v_mfma_f32_32x32x16_bf16 v[34:49], v[154:157], v[12:15], v[34:49]
	v_mfma_f32_32x32x16_bf16 v[50:65], v[166:169], v[4:7], v[50:65]
	s_waitcnt vmcnt(9)
	v_mfma_f32_32x32x16_bf16 v[34:49], v[150:153], v[4:7], v[34:49]
	v_mfma_f32_32x32x16_bf16 v[50:65], v[162:165], v[0:3], v[50:65]
	s_waitcnt vmcnt(8)
	v_mfma_f32_32x32x16_bf16 v[34:49], v[146:149], v[0:3], v[34:49]
	s_setprio 0
	s_cbranch_vccnz .LBB0_926
.LBB0_919:
	s_waitcnt vmcnt(0)
	s_setprio 1
	v_mfma_f32_32x32x16_bf16 v[66:81], v[142:145], v[98:101], 0
	s_mov_b32 s16, s44
	s_add_i32 s44, s44, 1
	s_cmp_ge_u32 s44, s5
	v_lshl_add_u64 v[0:1], v[202:203], 0, s[48:49]
	s_cselect_b64 s[50:51], -1, 0
	s_cmp_lt_u32 s44, s5
	global_load_dwordx4 v[174:177], v[0:1], off
	global_load_dwordx4 v[170:173], v[0:1], off offset:1024
	global_load_dwordx4 v[166:169], v[0:1], off offset:2048
	global_load_dwordx4 v[162:165], v[0:1], off offset:3072
	v_mfma_f32_32x32x16_bf16 v[82:97], v[126:129], v[98:101], 0
	v_add_co_u32_e32 v0, vcc, s79, v0
	s_cselect_b32 s16, s44, s16
	s_nop 0
	v_addc_co_u32_e32 v1, vcc, 0, v1, vcc
	s_lshl_b64 s[48:49], s[16:17], 13
	global_load_dwordx4 v[158:161], v[0:1], off
	global_load_dwordx4 v[154:157], v[0:1], off offset:1024
	global_load_dwordx4 v[150:153], v[0:1], off offset:2048
	global_load_dwordx4 v[146:149], v[0:1], off offset:3072
	v_mfma_f32_32x32x16_bf16 v[66:81], v[138:141], v[102:105], v[66:81]
	v_lshl_add_u64 v[0:1], v[184:185], 0, s[48:49]
	global_load_dwordx4 v[142:145], v[0:1], off
	global_load_dwordx4 v[138:141], v[0:1], off offset:1024
	s_cmp_le_u32 s33, s4
	s_cselect_b64 s[52:53], -1, 0
	s_cmp_gt_i32 s33, s6
	v_mfma_f32_32x32x16_bf16 v[82:97], v[122:125], v[102:105], v[82:97]
	v_mfma_f32_32x32x16_bf16 v[66:81], v[134:137], v[106:109], v[66:81]
	v_mfma_f32_32x32x16_bf16 v[82:97], v[118:121], v[106:109], v[82:97]
	v_mfma_f32_32x32x16_bf16 v[66:81], v[130:133], v[110:113], v[66:81]
	global_load_dwordx4 v[134:137], v[0:1], off offset:2048
	global_load_dwordx4 v[130:133], v[0:1], off offset:3072
	v_add_co_u32_e32 v0, vcc, s79, v0
	s_nop 1
	v_addc_co_u32_e32 v1, vcc, 0, v1, vcc
	global_load_dwordx4 v[126:129], v[0:1], off
	global_load_dwordx4 v[122:125], v[0:1], off offset:1024
	v_mfma_f32_32x32x16_bf16 v[82:97], v[114:117], v[110:113], v[82:97]
	s_setprio 0
	global_load_dwordx4 v[118:121], v[0:1], off offset:2048
	global_load_dwordx4 v[114:117], v[0:1], off offset:3072
	v_add_u32_e32 v0, s33, v212
	v_cvt_f32_i32_e32 v206, v0
	s_cselect_b64 vcc, -1, 0
	s_and_b64 vcc, s[52:53], vcc
	s_mov_b64 s[52:53], -1
	s_and_b64 vcc, exec, vcc
	s_cbranch_vccnz .LBB0_921
	v_add_f32_e32 v1, 1.0, v206
	v_cmp_le_f32_e64 vcc, |v206|, s91
	v_cmp_le_f32_e64 s[52:53], |v1|, s91
	v_fma_f32 v0, s46, -|v206|, v66
	v_fma_f32 v1, s46, -|v1|, v67
	v_cndmask_b32_e32 v0, v242, v0, vcc
	v_cndmask_b32_e64 v1, v242, v1, s[52:53]
	v_add_f32_e32 v2, 2.0, v206
	v_add_f32_e32 v3, 0x40400000, v206
	v_cmp_le_f32_e64 vcc, |v2|, s91
	v_cmp_le_f32_e64 s[52:53], |v3|, s91
	v_fma_f32 v2, s46, -|v2|, v68
	v_fma_f32 v3, s46, -|v3|, v69
	v_cndmask_b32_e32 v2, v242, v2, vcc
	v_cndmask_b32_e64 v3, v242, v3, s[52:53]
	v_add_f32_e32 v4, 0x41000000, v206
	v_add_f32_e32 v5, 0x41100000, v206
	v_cmp_le_f32_e64 vcc, |v4|, s91
	v_cmp_le_f32_e64 s[52:53], |v5|, s91
	v_fma_f32 v4, s46, -|v4|, v70
	v_fma_f32 v5, s46, -|v5|, v71
	v_cndmask_b32_e32 v4, v242, v4, vcc
	v_cndmask_b32_e64 v5, v242, v5, s[52:53]
	v_add_f32_e32 v6, 0x41200000, v206
	v_add_f32_e32 v7, 0x41300000, v206
	v_cmp_le_f32_e64 vcc, |v6|, s91
	v_cmp_le_f32_e64 s[52:53], |v7|, s91
	v_fma_f32 v6, s46, -|v6|, v72
	v_fma_f32 v7, s46, -|v7|, v73
	v_cndmask_b32_e32 v6, v242, v6, vcc
	v_cndmask_b32_e64 v7, v242, v7, s[52:53]
	v_add_f32_e32 v8, 0x41800000, v206
	v_add_f32_e32 v9, 0x41880000, v206
	v_cmp_le_f32_e64 vcc, |v8|, s91
	v_cmp_le_f32_e64 s[52:53], |v9|, s91
	v_fma_f32 v8, s46, -|v8|, v74
	v_fma_f32 v9, s46, -|v9|, v75
	v_cndmask_b32_e32 v8, v242, v8, vcc
	v_cndmask_b32_e64 v9, v242, v9, s[52:53]
	v_add_f32_e32 v10, 0x41900000, v206
	v_add_f32_e32 v11, 0x41980000, v206
	v_cmp_le_f32_e64 vcc, |v10|, s91
	v_cmp_le_f32_e64 s[52:53], |v11|, s91
	v_fma_f32 v10, s46, -|v10|, v76
	v_fma_f32 v11, s46, -|v11|, v77
	v_cndmask_b32_e32 v10, v242, v10, vcc
	v_cndmask_b32_e64 v11, v242, v11, s[52:53]
	v_add_f32_e32 v12, 0x41c00000, v206
	v_add_f32_e32 v13, 0x41c80000, v206
	v_cmp_le_f32_e64 vcc, |v12|, s91
	v_cmp_le_f32_e64 s[52:53], |v13|, s91
	v_fma_f32 v12, s46, -|v12|, v78
	v_fma_f32 v13, s46, -|v13|, v79
	v_cndmask_b32_e32 v12, v242, v12, vcc
	v_cndmask_b32_e64 v13, v242, v13, s[52:53]
	v_add_f32_e32 v14, 0x41d00000, v206
	v_add_f32_e32 v15, 0x41d80000, v206
	v_cmp_le_f32_e64 vcc, |v14|, s91
	v_cmp_le_f32_e64 s[52:53], |v15|, s91
	v_fma_f32 v14, s46, -|v14|, v80
	v_fma_f32 v15, s46, -|v15|, v81
	v_cndmask_b32_e32 v14, v242, v14, vcc
	v_cndmask_b32_e64 v15, v242, v15, s[52:53]
	v_add_f32_e32 v16, 0x42000000, v206
	v_add_f32_e32 v17, 0x42040000, v206
	v_cmp_le_f32_e64 vcc, |v16|, s91
	v_cmp_le_f32_e64 s[52:53], |v17|, s91
	v_fma_f32 v16, s46, -|v16|, v82
	v_fma_f32 v17, s46, -|v17|, v83
	v_cndmask_b32_e32 v16, v242, v16, vcc
	v_cndmask_b32_e64 v17, v242, v17, s[52:53]
	v_add_f32_e32 v18, 0x42080000, v206
	v_add_f32_e32 v19, 0x420c0000, v206
	v_cmp_le_f32_e64 vcc, |v18|, s91
	v_cmp_le_f32_e64 s[52:53], |v19|, s91
	v_fma_f32 v18, s46, -|v18|, v84
	v_fma_f32 v19, s46, -|v19|, v85
	v_cndmask_b32_e32 v18, v242, v18, vcc
	v_cndmask_b32_e64 v19, v242, v19, s[52:53]
	v_add_f32_e32 v20, 0x42200000, v206
	v_add_f32_e32 v21, 0x42240000, v206
	v_cmp_le_f32_e64 vcc, |v20|, s91
	v_cmp_le_f32_e64 s[52:53], |v21|, s91
	v_fma_f32 v20, s46, -|v20|, v86
	v_fma_f32 v21, s46, -|v21|, v87
	v_cndmask_b32_e32 v20, v242, v20, vcc
	v_cndmask_b32_e64 v21, v242, v21, s[52:53]
	v_add_f32_e32 v22, 0x42280000, v206
	v_add_f32_e32 v23, 0x422c0000, v206
	v_cmp_le_f32_e64 vcc, |v22|, s91
	v_cmp_le_f32_e64 s[52:53], |v23|, s91
	v_fma_f32 v22, s46, -|v22|, v88
	v_fma_f32 v23, s46, -|v23|, v89
	v_cndmask_b32_e32 v22, v242, v22, vcc
	v_cndmask_b32_e64 v23, v242, v23, s[52:53]
	v_add_f32_e32 v24, 0x42400000, v206
	v_add_f32_e32 v25, 0x42440000, v206
	v_cmp_le_f32_e64 vcc, |v24|, s91
	v_cmp_le_f32_e64 s[52:53], |v25|, s91
	v_fma_f32 v24, s46, -|v24|, v90
	v_fma_f32 v25, s46, -|v25|, v91
	v_cndmask_b32_e32 v24, v242, v24, vcc
	v_cndmask_b32_e64 v25, v242, v25, s[52:53]
	v_add_f32_e32 v26, 0x42480000, v206
	v_add_f32_e32 v27, 0x424c0000, v206
	v_cmp_le_f32_e64 vcc, |v26|, s91
	v_cmp_le_f32_e64 s[52:53], |v27|, s91
	v_fma_f32 v26, s46, -|v26|, v92
	v_fma_f32 v27, s46, -|v27|, v93
	v_cndmask_b32_e32 v26, v242, v26, vcc
	v_cndmask_b32_e64 v27, v242, v27, s[52:53]
	v_add_f32_e32 v28, 0x42600000, v206
	v_add_f32_e32 v29, 0x42640000, v206
	v_cmp_le_f32_e64 vcc, |v28|, s91
	v_cmp_le_f32_e64 s[52:53], |v29|, s91
	v_fma_f32 v28, s46, -|v28|, v94
	v_fma_f32 v29, s46, -|v29|, v95
	v_cndmask_b32_e32 v28, v242, v28, vcc
	v_cndmask_b32_e64 v29, v242, v29, s[52:53]
	v_add_f32_e32 v30, 0x42680000, v206
	v_add_f32_e32 v31, 0x426c0000, v206
	v_cmp_le_f32_e64 vcc, |v30|, s91
	v_cmp_le_f32_e64 s[52:53], |v31|, s91
	v_fma_f32 v30, s46, -|v30|, v96
	v_fma_f32 v31, s46, -|v31|, v97
	v_cndmask_b32_e32 v30, v242, v30, vcc
	v_cndmask_b32_e64 v31, v242, v31, s[52:53]
	s_mov_b64 s[52:53], 0
